# P0 row-conversion loop and final rmsnorm loop: issue all loads of a row together with counted vmcnt waits (were 4 serialized round trips per row)
# speedup vs baseline: 1.0119x; 1.0028x over previous
; __device__ __forceinline__ unsigned pk2(float lo, float hi) { f32x2 v = {lo, hi}; bf16x2_t b = __builtin_convertvector(v, bf16x2_t); return __builtin_bit_cast(unsigned, b); }
; __device__ __forceinline__ void p0_phase(const Args& a, LAS unsigned char* lds, int G, int wg, int part, bool split) {
;     ...
;     for (int m = gw; m < MT; m += NGW) {
;         const f32x4* xr = (const f32x4*)(x + (size_t)m * DM) + lane; float s = 0.f;
;         unsigned long long* o8 = (unsigned long long*)(xb + (size_t)m * DM) + lane;
; #pragma unroll
;         for (int j = 0; j < 4; ++j) { const f32x4 v = xr[64 * j]; s += (v.x * v.x + v.y * v.y) + (v.z * v.z + v.w * v.w);
;             o8[64 * j] = (unsigned long long)pk2(v.x, v.y) | ((unsigned long long)pk2(v.z, v.w) << 32); }
;         s = wave_sum(s);
;         if (lane < 16) ssq[(size_t)m * 16 + lane] = (lane == 0) ? s : 0.f;
;     }
.LBB0_126:
	s_waitcnt lgkmcnt(0)
	global_load_dwordx4 v[12:15], v[4:5], off offset:-3072
	global_load_dwordx4 v[16:19], v[4:5], off offset:-2048
	global_load_dwordx4 v[20:23], v[4:5], off offset:-1024
	global_load_dwordx4 v[24:27], v[4:5], off
	s_waitcnt vmcnt(3)
	v_cvt_pk_bf16_f32 v28, v12, v13
	v_cvt_pk_bf16_f32 v29, v14, v15
	global_store_dwordx2 v[2:3], v[28:29], off offset:-1024
	v_mul_f32_e32 v13, v13, v13
	v_mul_f32_e32 v15, v15, v15
	v_fmac_f32_e32 v13, v12, v12
	v_fmac_f32_e32 v15, v14, v14
	v_add_f32_e32 v12, v13, v15
	s_waitcnt vmcnt(3)
	v_cvt_pk_bf16_f32 v30, v16, v17
	v_cvt_pk_bf16_f32 v31, v18, v19
	global_store_dwordx2 v[2:3], v[30:31], off offset:-512
	v_mul_f32_e32 v13, v17, v17
	v_mul_f32_e32 v14, v19, v19
	v_fmac_f32_e32 v13, v16, v16
	v_fmac_f32_e32 v14, v18, v18
	v_add_f32_e32 v13, v13, v14
	v_add_f32_e32 v12, v12, v13
	s_waitcnt vmcnt(3)
	v_cvt_pk_bf16_f32 v32, v20, v21
	v_cvt_pk_bf16_f32 v33, v22, v23
	global_store_dwordx2 v[2:3], v[32:33], off
	v_mul_f32_e32 v13, v21, v21
	v_mul_f32_e32 v14, v23, v23
	v_fmac_f32_e32 v13, v20, v20
	v_fmac_f32_e32 v14, v22, v22
	v_add_f32_e32 v13, v13, v14
	v_add_f32_e32 v12, v12, v13
	s_waitcnt vmcnt(3)
	v_mul_f32_e32 v13, v25, v25
	v_mul_f32_e32 v14, v27, v27
	v_fmac_f32_e32 v13, v24, v24
	v_fmac_f32_e32 v14, v26, v26
	v_add_f32_e32 v13, v13, v14
	v_add_f32_e32 v12, v12, v13
	ds_bpermute_b32 v13, v6, v12
	v_cvt_pk_bf16_f32 v14, v24, v25
	v_cvt_pk_bf16_f32 v15, v26, v27
	global_store_dwordx2 v[2:3], v[14:15], off offset:512
	s_waitcnt lgkmcnt(0)
	v_add_f32_e32 v12, v12, v13
	ds_bpermute_b32 v13, v7, v12
	s_waitcnt lgkmcnt(0)
	v_add_f32_e32 v12, v12, v13
	ds_bpermute_b32 v13, v8, v12
	s_waitcnt lgkmcnt(0)
	v_add_f32_e32 v12, v12, v13
	ds_bpermute_b32 v13, v9, v12
	s_waitcnt lgkmcnt(0)
	v_add_f32_e32 v12, v12, v13
	ds_bpermute_b32 v13, v10, v12
	s_waitcnt lgkmcnt(0)
	v_add_f32_e32 v12, v12, v13
	ds_bpermute_b32 v13, v11, v12
	s_and_saveexec_b64 s[6:7], vcc
	s_cbranch_execz .LBB0_125
	s_waitcnt lgkmcnt(0)
	v_add_f32_e32 v12, v12, v13
	v_cndmask_b32_e64 v12, 0, v12, s[4:5]
	global_store_dword v[0:1], v12, off
	s_branch .LBB0_125

; __device__ __forceinline__ float ssq_row(const float* part, int row) {
;     const f32x4* p = (const f32x4*)(part + (size_t)row * 16);
;     const f32x4 a = p[0], b = p[1], c = p[2], d = p[3];
;     return (((a[0] + a[1]) + (a[2] + a[3])) + ((b[0] + b[1]) + (b[2] + b[3]))) + (((c[0] + c[1]) + (c[2] + c[3])) + ((d[0] + d[1]) + (d[2] + d[3])));
; }
; __device__ __forceinline__ void final_phase(const bf16_t* xb, float* out, const float* ssq, const float* gain, int G, int wg) {
;     ...
;     for (int m = gw; m < MT; m += NGW) {
;         const float rs = __builtin_amdgcn_rsqf(pg8::ssq_row(ssq, m) * (1.f / 1024.f) + EPS);
;         const u32x2* xr = (const u32x2*)(xb + (size_t)m * DM) + lane; f32x4* orow = (f32x4*)(out + (size_t)m * DM) + lane;
; #pragma unroll
;         for (int j = 0; j < 4; ++j) { const u32x2 w = xr[64 * j];
;             const f32x4 v = {__builtin_bit_cast(float, w.x << 16), __builtin_bit_cast(float, w.x & 0xffff0000u), __builtin_bit_cast(float, w.y << 16), __builtin_bit_cast(float, w.y & 0xffff0000u)};
;             orow[64 * j] = v * rs * gv[j]; }
;     }
.LBB0_1927:
	global_load_dwordx4 v[24:27], v[16:17], off offset:-32
	global_load_dwordx4 v[28:31], v[16:17], off
	global_load_dwordx4 v[32:35], v[16:17], off offset:-16
	global_load_dwordx4 v[36:39], v[16:17], off offset:16
	global_load_dwordx2 v[40:41], v[20:21], off offset:-1024
	global_load_dwordx2 v[44:45], v[20:21], off offset:-512
	global_load_dwordx2 v[46:47], v[20:21], off
	global_load_dwordx2 v[48:49], v[20:21], off offset:512
	v_add_u32_e32 v22, s12, v22
	v_cmp_lt_i32_e32 vcc, s8, v22
	v_lshl_add_u64 v[16:17], v[16:17], 0, s[2:3]
	v_lshl_add_u64 v[20:21], v[20:21], 0, s[6:7]
	s_or_b64 s[10:11], vcc, s[10:11]
	s_waitcnt vmcnt(7)
	v_mov_b32_e32 v42, v24
	s_waitcnt vmcnt(6)
	v_mov_b32_e32 v43, v28
	v_mov_b32_e32 v28, v25
	v_mov_b32_e32 v24, v26
	v_mov_b32_e32 v25, v30
	v_mov_b32_e32 v30, v27
	s_waitcnt vmcnt(5)
	v_mov_b32_e32 v26, v32
	s_waitcnt vmcnt(4)
	v_mov_b32_e32 v27, v36
	v_mov_b32_e32 v36, v33
	v_mov_b32_e32 v32, v34
	v_mov_b32_e32 v33, v38
	v_mov_b32_e32 v38, v35
	v_pk_add_f32 v[28:29], v[42:43], v[28:29]
	v_pk_add_f32 v[24:25], v[24:25], v[30:31]
	v_pk_add_f32 v[26:27], v[26:27], v[36:37]
	v_pk_add_f32 v[30:31], v[32:33], v[38:39]
	v_pk_add_f32 v[24:25], v[28:29], v[24:25]
	v_pk_add_f32 v[26:27], v[26:27], v[30:31]
	s_waitcnt vmcnt(3)
	v_lshlrev_b32_e32 v34, 16, v40
	v_pk_add_f32 v[24:25], v[24:25], v[26:27]
	v_and_b32_e32 v35, 0xffff0000, v40
	v_add_f32_e32 v24, v24, v25
	v_fmamk_f32 v24, v24, 0x3a800000, v23
	v_rsq_f32_e32 v28, v24
	v_lshlrev_b32_e32 v40, 16, v41
	v_and_b32_e32 v41, 0xffff0000, v41
	v_pk_mul_f32 v[24:25], v[28:29], v[34:35] op_sel_hi:[0,1]
	v_pk_mul_f32 v[26:27], v[28:29], v[40:41] op_sel_hi:[0,1]
	v_pk_mul_f32 v[26:27], v[2:3], v[26:27]
	v_pk_mul_f32 v[24:25], v[0:1], v[24:25]
	global_store_dwordx4 v[18:19], v[24:27], off offset:-2048
	s_waitcnt vmcnt(3)
	s_nop 1
	v_lshlrev_b32_e32 v26, 16, v44
	v_and_b32_e32 v27, 0xffff0000, v44
	v_lshlrev_b32_e32 v24, 16, v45
	v_and_b32_e32 v25, 0xffff0000, v45
	v_pk_mul_f32 v[30:31], v[28:29], v[26:27] op_sel_hi:[0,1]
	v_pk_mul_f32 v[24:25], v[28:29], v[24:25] op_sel_hi:[0,1]
	v_pk_mul_f32 v[26:27], v[6:7], v[24:25]
	v_pk_mul_f32 v[24:25], v[4:5], v[30:31]
	global_store_dwordx4 v[18:19], v[24:27], off offset:-1024
	s_waitcnt vmcnt(3)
	s_nop 1
	v_lshlrev_b32_e32 v26, 16, v46
	v_and_b32_e32 v27, 0xffff0000, v46
	v_lshlrev_b32_e32 v24, 16, v47
	v_and_b32_e32 v25, 0xffff0000, v47
	v_pk_mul_f32 v[30:31], v[28:29], v[26:27] op_sel_hi:[0,1]
	v_pk_mul_f32 v[24:25], v[28:29], v[24:25] op_sel_hi:[0,1]
	v_pk_mul_f32 v[26:27], v[10:11], v[24:25]
	v_pk_mul_f32 v[24:25], v[8:9], v[30:31]
	global_store_dwordx4 v[18:19], v[24:27], off
	s_waitcnt vmcnt(3)
	s_nop 1
	v_lshlrev_b32_e32 v26, 16, v48
	v_and_b32_e32 v27, 0xffff0000, v48
	v_lshlrev_b32_e32 v24, 16, v49
	v_and_b32_e32 v25, 0xffff0000, v49
	v_pk_mul_f32 v[30:31], v[28:29], v[26:27] op_sel_hi:[0,1]
	v_pk_mul_f32 v[24:25], v[28:29], v[24:25] op_sel_hi:[0,1]
	v_pk_mul_f32 v[26:27], v[14:15], v[24:25]
	v_pk_mul_f32 v[24:25], v[12:13], v[30:31]
	global_store_dwordx4 v[18:19], v[24:27], off offset:1024
	v_lshl_add_u64 v[18:19], v[18:19], 0, s[4:5]
	s_andn2_b64 exec, exec, s[10:11]
	s_cbranch_execnz .LBB0_1927
